# softmax row sums with v_pk_add_f32 (16 packed adds instead of 32 scalar)
# baseline (speedup 1.0000x reference)
.LBB0_637:
	s_mulk_i32 s24, 0x5000
	v_add_u32_e32 v32, s24, v194
	s_setprio 1
	ds_read_b64_tr_b16 v[214:215], v32 offset:18432
	ds_read_b64_tr_b16 v[216:217], v32 offset:20992
	ds_read_b64_tr_b16 v[218:219], v32 offset:18496
	ds_read_b64_tr_b16 v[220:221], v32 offset:21056
	ds_read_b64_tr_b16 v[222:223], v32 offset:18560
	ds_read_b64_tr_b16 v[224:225], v32 offset:21120
	ds_read_b64_tr_b16 v[226:227], v32 offset:18624
	ds_read_b64_tr_b16 v[228:229], v32 offset:21184
	ds_read_b64_tr_b16 v[230:231], v32 offset:23552
	ds_read_b64_tr_b16 v[232:233], v32 offset:26112
	v_exp_f32_e32 v114, v114
	v_exp_f32_e32 v115, v115
	v_exp_f32_e32 v116, v116
	v_exp_f32_e32 v117, v117
	v_exp_f32_e32 v118, v118
	v_cvt_pk_bf16_f32 v234, v114, v115
	v_exp_f32_e32 v119, v119
	v_cvt_pk_bf16_f32 v235, v116, v117
	v_exp_f32_e32 v120, v120
	v_exp_f32_e32 v121, v121
	v_cvt_pk_bf16_f32 v236, v118, v119
	s_nop 0
	v_cvt_pk_bf16_f32 v237, v120, v121
	s_nop 1
	s_waitcnt lgkmcnt(8)
	v_mfma_f32_32x32x16_bf16 v[82:97], v[234:237], v[214:217], v[82:97]
	ds_read_b64_tr_b16 v[214:215], v32 offset:23616
	ds_read_b64_tr_b16 v[216:217], v32 offset:26176
	v_exp_f32_e32 v122, v122
	v_exp_f32_e32 v123, v123
	v_exp_f32_e32 v124, v124
	s_waitcnt lgkmcnt(8)
	v_mfma_f32_32x32x16_bf16 v[66:81], v[234:237], v[218:221], v[66:81]
	ds_read_b64_tr_b16 v[218:219], v32 offset:23680
	ds_read_b64_tr_b16 v[220:221], v32 offset:26240
	v_exp_f32_e32 v125, v125
	v_exp_f32_e32 v126, v126
	v_exp_f32_e32 v127, v127
	v_cvt_pk_bf16_f32 v238, v122, v123
	v_pk_add_f32 v[252:253], v[114:115], v[116:117]
	s_waitcnt lgkmcnt(8)
	v_mfma_f32_32x32x16_bf16 v[50:65], v[234:237], v[222:225], v[50:65]
	ds_read_b64_tr_b16 v[222:223], v32 offset:23744
	ds_read_b64_tr_b16 v[224:225], v32 offset:26304
	v_exp_f32_e32 v128, v128
	v_exp_f32_e32 v129, v129
	v_cvt_pk_bf16_f32 v239, v124, v125
	v_pk_add_f32 v[252:253], v[252:253], v[118:119]
	s_waitcnt lgkmcnt(8)
	v_mfma_f32_32x32x16_bf16 v[34:49], v[234:237], v[226:229], v[34:49]
	ds_read_b64_tr_b16 v[226:227], v32 offset:28672
	ds_read_b64_tr_b16 v[228:229], v32 offset:31232
	v_cvt_pk_bf16_f32 v240, v126, v127
	v_cvt_pk_bf16_f32 v241, v128, v129
	v_pk_add_f32 v[252:253], v[252:253], v[120:121]
	s_waitcnt lgkmcnt(8)
	v_mfma_f32_32x32x16_bf16 v[82:97], v[238:241], v[230:233], v[82:97]
	ds_read_b64_tr_b16 v[230:231], v32 offset:28736
	ds_read_b64_tr_b16 v[232:233], v32 offset:31296
	v_exp_f32_e32 v130, v130
	v_exp_f32_e32 v131, v131
	v_exp_f32_e32 v132, v132
	v_pk_add_f32 v[252:253], v[252:253], v[122:123]
	s_waitcnt lgkmcnt(8)
	v_mfma_f32_32x32x16_bf16 v[66:81], v[238:241], v[214:217], v[66:81]
	ds_read_b64_tr_b16 v[214:215], v32 offset:28800
	ds_read_b64_tr_b16 v[216:217], v32 offset:31360
	v_exp_f32_e32 v133, v133
	v_exp_f32_e32 v134, v134
	v_exp_f32_e32 v135, v135
	v_cvt_pk_bf16_f32 v244, v130, v131
	v_pk_add_f32 v[252:253], v[252:253], v[124:125]
	s_waitcnt lgkmcnt(8)
	v_mfma_f32_32x32x16_bf16 v[50:65], v[238:241], v[218:221], v[50:65]
	ds_read_b64_tr_b16 v[218:219], v32 offset:28864
	ds_read_b64_tr_b16 v[220:221], v32 offset:31424
	v_exp_f32_e32 v136, v136
	v_exp_f32_e32 v137, v137
	v_cvt_pk_bf16_f32 v245, v132, v133
	v_pk_add_f32 v[252:253], v[252:253], v[126:127]
	v_pk_add_f32 v[252:253], v[252:253], v[128:129]
	s_waitcnt lgkmcnt(8)
	v_mfma_f32_32x32x16_bf16 v[34:49], v[238:241], v[222:225], v[34:49]
	ds_read_b64_tr_b16 v[222:223], v32 offset:33792
	ds_read_b64_tr_b16 v[224:225], v32 offset:36352
	v_cvt_pk_bf16_f32 v246, v134, v135
	v_cvt_pk_bf16_f32 v247, v136, v137
	s_waitcnt lgkmcnt(8)
	v_mfma_f32_32x32x16_bf16 v[82:97], v[244:247], v[226:229], v[82:97]
	ds_read_b64_tr_b16 v[226:227], v32 offset:33856
	ds_read_b64_tr_b16 v[228:229], v32 offset:36416
	v_exp_f32_e32 v138, v138
	v_exp_f32_e32 v139, v139
	v_exp_f32_e32 v140, v140
	v_pk_add_f32 v[252:253], v[252:253], v[130:131]
	s_waitcnt lgkmcnt(8)
	v_mfma_f32_32x32x16_bf16 v[66:81], v[244:247], v[230:233], v[66:81]
	ds_read_b64_tr_b16 v[230:231], v32 offset:33920
	ds_read_b64_tr_b16 v[232:233], v32 offset:36480
	v_exp_f32_e32 v141, v141
	v_exp_f32_e32 v142, v142
	v_exp_f32_e32 v143, v143
	v_cvt_pk_bf16_f32 v248, v138, v139
	v_pk_add_f32 v[252:253], v[252:253], v[132:133]
	s_waitcnt lgkmcnt(8)
	v_mfma_f32_32x32x16_bf16 v[50:65], v[244:247], v[214:217], v[50:65]
	ds_read_b64_tr_b16 v[214:215], v32 offset:33984
	ds_read_b64_tr_b16 v[216:217], v32 offset:36544
	v_exp_f32_e32 v144, v144
	v_exp_f32_e32 v145, v145
	v_cvt_pk_bf16_f32 v249, v140, v141
	v_pk_add_f32 v[252:253], v[252:253], v[134:135]
	v_pk_add_f32 v[252:253], v[252:253], v[136:137]
	s_waitcnt lgkmcnt(8)
	v_mfma_f32_32x32x16_bf16 v[34:49], v[244:247], v[218:221], v[34:49]
	v_cvt_pk_bf16_f32 v250, v142, v143
	v_cvt_pk_bf16_f32 v251, v144, v145
	s_waitcnt lgkmcnt(6)
	v_mfma_f32_32x32x16_bf16 v[82:97], v[248:251], v[222:225], v[82:97]
	v_pk_add_f32 v[252:253], v[252:253], v[138:139]
	v_pk_add_f32 v[252:253], v[252:253], v[140:141]
	v_pk_add_f32 v[252:253], v[252:253], v[142:143]
	s_waitcnt lgkmcnt(4)
	v_mfma_f32_32x32x16_bf16 v[66:81], v[248:251], v[226:229], v[66:81]
	v_pk_add_f32 v[252:253], v[252:253], v[144:145]
	s_waitcnt lgkmcnt(2)
	v_mfma_f32_32x32x16_bf16 v[50:65], v[248:251], v[230:233], v[50:65]
	v_add_f32_e32 v252, v252, v253
	s_waitcnt lgkmcnt(0)
	v_mfma_f32_32x32x16_bf16 v[34:49], v[248:251], v[214:217], v[34:49]
	v_add_f32_e32 v182, v182, v252
	s_setprio 0

.LBB0_837:
	s_mulk_i32 s35, 0x5000
	v_add_u32_e32 v32, s35, v194
	s_setprio 1
	ds_read_b64_tr_b16 v[214:215], v32 offset:18432
	ds_read_b64_tr_b16 v[216:217], v32 offset:20992
	ds_read_b64_tr_b16 v[218:219], v32 offset:18496
	ds_read_b64_tr_b16 v[220:221], v32 offset:21056
	ds_read_b64_tr_b16 v[222:223], v32 offset:18560
	ds_read_b64_tr_b16 v[224:225], v32 offset:21120
	ds_read_b64_tr_b16 v[226:227], v32 offset:18624
	ds_read_b64_tr_b16 v[228:229], v32 offset:21184
	ds_read_b64_tr_b16 v[230:231], v32 offset:23552
	ds_read_b64_tr_b16 v[232:233], v32 offset:26112
	v_exp_f32_e32 v114, v114
	v_exp_f32_e32 v115, v115
	v_exp_f32_e32 v116, v116
	v_exp_f32_e32 v117, v117
	v_exp_f32_e32 v118, v118
	v_cvt_pk_bf16_f32 v234, v114, v115
	v_exp_f32_e32 v119, v119
	v_cvt_pk_bf16_f32 v235, v116, v117
	v_exp_f32_e32 v120, v120
	v_exp_f32_e32 v121, v121
	v_cvt_pk_bf16_f32 v236, v118, v119
	s_nop 0
	v_cvt_pk_bf16_f32 v237, v120, v121
	s_nop 1
	s_waitcnt lgkmcnt(8)
	v_mfma_f32_32x32x16_bf16 v[82:97], v[234:237], v[214:217], v[82:97]
	ds_read_b64_tr_b16 v[214:215], v32 offset:23616
	ds_read_b64_tr_b16 v[216:217], v32 offset:26176
	v_exp_f32_e32 v122, v122
	v_exp_f32_e32 v123, v123
	v_exp_f32_e32 v124, v124
	s_waitcnt lgkmcnt(8)
	v_mfma_f32_32x32x16_bf16 v[66:81], v[234:237], v[218:221], v[66:81]
	ds_read_b64_tr_b16 v[218:219], v32 offset:23680
	ds_read_b64_tr_b16 v[220:221], v32 offset:26240
	v_exp_f32_e32 v125, v125
	v_exp_f32_e32 v126, v126
	v_exp_f32_e32 v127, v127
	v_cvt_pk_bf16_f32 v238, v122, v123
	v_pk_add_f32 v[252:253], v[114:115], v[116:117]
	s_waitcnt lgkmcnt(8)
	v_mfma_f32_32x32x16_bf16 v[50:65], v[234:237], v[222:225], v[50:65]
	ds_read_b64_tr_b16 v[222:223], v32 offset:23744
	ds_read_b64_tr_b16 v[224:225], v32 offset:26304
	v_exp_f32_e32 v128, v128
	v_exp_f32_e32 v129, v129
	v_cvt_pk_bf16_f32 v239, v124, v125
	v_pk_add_f32 v[252:253], v[252:253], v[118:119]
	s_waitcnt lgkmcnt(8)
	v_mfma_f32_32x32x16_bf16 v[34:49], v[234:237], v[226:229], v[34:49]
	ds_read_b64_tr_b16 v[226:227], v32 offset:28672
	ds_read_b64_tr_b16 v[228:229], v32 offset:31232
	v_cvt_pk_bf16_f32 v240, v126, v127
	v_cvt_pk_bf16_f32 v241, v128, v129
	v_pk_add_f32 v[252:253], v[252:253], v[120:121]
	s_waitcnt lgkmcnt(8)
	v_mfma_f32_32x32x16_bf16 v[82:97], v[238:241], v[230:233], v[82:97]
	ds_read_b64_tr_b16 v[230:231], v32 offset:28736
	ds_read_b64_tr_b16 v[232:233], v32 offset:31296
	v_exp_f32_e32 v130, v130
	v_exp_f32_e32 v131, v131
	v_exp_f32_e32 v132, v132
	v_pk_add_f32 v[252:253], v[252:253], v[122:123]
	s_waitcnt lgkmcnt(8)
	v_mfma_f32_32x32x16_bf16 v[66:81], v[238:241], v[214:217], v[66:81]
	ds_read_b64_tr_b16 v[214:215], v32 offset:28800
	ds_read_b64_tr_b16 v[216:217], v32 offset:31360
	v_exp_f32_e32 v133, v133
	v_exp_f32_e32 v134, v134
	v_exp_f32_e32 v135, v135
	v_cvt_pk_bf16_f32 v244, v130, v131
	v_pk_add_f32 v[252:253], v[252:253], v[124:125]
	s_waitcnt lgkmcnt(8)
	v_mfma_f32_32x32x16_bf16 v[50:65], v[238:241], v[218:221], v[50:65]
	ds_read_b64_tr_b16 v[218:219], v32 offset:28864
	ds_read_b64_tr_b16 v[220:221], v32 offset:31424
	v_exp_f32_e32 v136, v136
	v_exp_f32_e32 v137, v137
	v_cvt_pk_bf16_f32 v245, v132, v133
	v_pk_add_f32 v[252:253], v[252:253], v[126:127]
	v_pk_add_f32 v[252:253], v[252:253], v[128:129]
	s_waitcnt lgkmcnt(8)
	v_mfma_f32_32x32x16_bf16 v[34:49], v[238:241], v[222:225], v[34:49]
	ds_read_b64_tr_b16 v[222:223], v32 offset:33792
	ds_read_b64_tr_b16 v[224:225], v32 offset:36352
	v_cvt_pk_bf16_f32 v246, v134, v135
	v_cvt_pk_bf16_f32 v247, v136, v137
	s_waitcnt lgkmcnt(8)
	v_mfma_f32_32x32x16_bf16 v[82:97], v[244:247], v[226:229], v[82:97]
	ds_read_b64_tr_b16 v[226:227], v32 offset:33856
	ds_read_b64_tr_b16 v[228:229], v32 offset:36416
	v_exp_f32_e32 v138, v138
	v_exp_f32_e32 v139, v139
	v_exp_f32_e32 v140, v140
	v_pk_add_f32 v[252:253], v[252:253], v[130:131]
	s_waitcnt lgkmcnt(8)
	v_mfma_f32_32x32x16_bf16 v[66:81], v[244:247], v[230:233], v[66:81]
	ds_read_b64_tr_b16 v[230:231], v32 offset:33920
	ds_read_b64_tr_b16 v[232:233], v32 offset:36480
	v_exp_f32_e32 v141, v141
	v_exp_f32_e32 v142, v142
	v_exp_f32_e32 v143, v143
	v_cvt_pk_bf16_f32 v248, v138, v139
	v_pk_add_f32 v[252:253], v[252:253], v[132:133]
	s_waitcnt lgkmcnt(8)
	v_mfma_f32_32x32x16_bf16 v[50:65], v[244:247], v[214:217], v[50:65]
	ds_read_b64_tr_b16 v[214:215], v32 offset:33984
	ds_read_b64_tr_b16 v[216:217], v32 offset:36544
	v_exp_f32_e32 v144, v144
	v_exp_f32_e32 v145, v145
	v_cvt_pk_bf16_f32 v249, v140, v141
	v_pk_add_f32 v[252:253], v[252:253], v[134:135]
	v_pk_add_f32 v[252:253], v[252:253], v[136:137]
	s_waitcnt lgkmcnt(8)
	v_mfma_f32_32x32x16_bf16 v[34:49], v[244:247], v[218:221], v[34:49]
	v_cvt_pk_bf16_f32 v250, v142, v143
	v_cvt_pk_bf16_f32 v251, v144, v145
	s_waitcnt lgkmcnt(6)
	v_mfma_f32_32x32x16_bf16 v[82:97], v[248:251], v[222:225], v[82:97]
	v_pk_add_f32 v[252:253], v[252:253], v[138:139]
	v_pk_add_f32 v[252:253], v[252:253], v[140:141]
	v_pk_add_f32 v[252:253], v[252:253], v[142:143]
	s_waitcnt lgkmcnt(4)
	v_mfma_f32_32x32x16_bf16 v[66:81], v[248:251], v[226:229], v[66:81]
	v_pk_add_f32 v[252:253], v[252:253], v[144:145]
	s_waitcnt lgkmcnt(2)
	v_mfma_f32_32x32x16_bf16 v[50:65], v[248:251], v[230:233], v[50:65]
	v_add_f32_e32 v252, v252, v253
	s_waitcnt lgkmcnt(0)
	v_mfma_f32_32x32x16_bf16 v[34:49], v[248:251], v[214:217], v[34:49]
	v_add_f32_e32 v182, v182, v252
	s_setprio 0

.LBB0_2167:
	s_mulk_i32 s78, 0x5000
	v_add_u32_e32 v0, s78, v203
	v_add_u32_e32 v3, 0xc800, v0
	s_setprio 1
	ds_read_b64_tr_b16 v[214:215], v0 offset:51200
	ds_read_b64_tr_b16 v[216:217], v0 offset:53760
	ds_read_b64_tr_b16 v[218:219], v0 offset:51264
	ds_read_b64_tr_b16 v[220:221], v0 offset:53824
	ds_read_b64_tr_b16 v[222:223], v0 offset:51328
	ds_read_b64_tr_b16 v[224:225], v0 offset:53888
	ds_read_b64_tr_b16 v[226:227], v0 offset:51392
	ds_read_b64_tr_b16 v[228:229], v0 offset:53952
	ds_read_b64_tr_b16 v[230:231], v0 offset:56320
	ds_read_b64_tr_b16 v[232:233], v0 offset:58880
	v_exp_f32_e32 v96, v96
	v_exp_f32_e32 v97, v97
	v_exp_f32_e32 v98, v98
	v_exp_f32_e32 v99, v99
	v_exp_f32_e32 v100, v100
	v_cvt_pk_bf16_f32 v234, v96, v97
	v_exp_f32_e32 v101, v101
	v_cvt_pk_bf16_f32 v235, v98, v99
	v_exp_f32_e32 v102, v102
	v_exp_f32_e32 v103, v103
	v_cvt_pk_bf16_f32 v236, v100, v101
	s_nop 0
	v_cvt_pk_bf16_f32 v237, v102, v103
	s_nop 1
	s_waitcnt lgkmcnt(8)
	v_mfma_f32_32x32x16_bf16 v[64:79], v[234:237], v[214:217], v[64:79]
	ds_read_b64_tr_b16 v[214:215], v0 offset:56384
	ds_read_b64_tr_b16 v[216:217], v0 offset:58944
	v_exp_f32_e32 v104, v104
	v_exp_f32_e32 v105, v105
	v_exp_f32_e32 v106, v106
	s_waitcnt lgkmcnt(8)
	v_mfma_f32_32x32x16_bf16 v[48:63], v[234:237], v[218:221], v[48:63]
	ds_read_b64_tr_b16 v[218:219], v0 offset:56448
	ds_read_b64_tr_b16 v[220:221], v0 offset:59008
	v_exp_f32_e32 v107, v107
	v_exp_f32_e32 v108, v108
	v_exp_f32_e32 v109, v109
	v_cvt_pk_bf16_f32 v238, v104, v105
	v_pk_add_f32 v[252:253], v[96:97], v[98:99]
	s_waitcnt lgkmcnt(8)
	v_mfma_f32_32x32x16_bf16 v[32:47], v[234:237], v[222:225], v[32:47]
	ds_read_b64_tr_b16 v[222:223], v0 offset:56512
	ds_read_b64_tr_b16 v[224:225], v0 offset:59072
	v_exp_f32_e32 v110, v110
	v_exp_f32_e32 v111, v111
	v_cvt_pk_bf16_f32 v239, v106, v107
	v_pk_add_f32 v[252:253], v[252:253], v[100:101]
	s_waitcnt lgkmcnt(8)
	v_mfma_f32_32x32x16_bf16 v[16:31], v[234:237], v[226:229], v[16:31]
	ds_read_b64_tr_b16 v[226:227], v0 offset:61440
	ds_read_b64_tr_b16 v[228:229], v0 offset:64000
	v_cvt_pk_bf16_f32 v240, v108, v109
	v_cvt_pk_bf16_f32 v241, v110, v111
	v_pk_add_f32 v[252:253], v[252:253], v[102:103]
	s_waitcnt lgkmcnt(8)
	v_mfma_f32_32x32x16_bf16 v[64:79], v[238:241], v[230:233], v[64:79]
	ds_read_b64_tr_b16 v[230:231], v0 offset:61504
	ds_read_b64_tr_b16 v[232:233], v0 offset:64064
	v_exp_f32_e32 v112, v112
	v_exp_f32_e32 v113, v113
	v_exp_f32_e32 v114, v114
	v_pk_add_f32 v[252:253], v[252:253], v[104:105]
	s_waitcnt lgkmcnt(8)
	v_mfma_f32_32x32x16_bf16 v[48:63], v[238:241], v[214:217], v[48:63]
	ds_read_b64_tr_b16 v[214:215], v0 offset:61568
	ds_read_b64_tr_b16 v[216:217], v0 offset:64128
	v_exp_f32_e32 v115, v115
	v_exp_f32_e32 v116, v116
	v_exp_f32_e32 v117, v117
	v_cvt_pk_bf16_f32 v244, v112, v113
	v_pk_add_f32 v[252:253], v[252:253], v[106:107]
	s_waitcnt lgkmcnt(8)
	v_mfma_f32_32x32x16_bf16 v[32:47], v[238:241], v[218:221], v[32:47]
	ds_read_b64_tr_b16 v[218:219], v0 offset:61632
	ds_read_b64_tr_b16 v[220:221], v0 offset:64192
	v_exp_f32_e32 v118, v118
	v_exp_f32_e32 v119, v119
	v_cvt_pk_bf16_f32 v245, v114, v115
	v_pk_add_f32 v[252:253], v[252:253], v[108:109]
	v_pk_add_f32 v[252:253], v[252:253], v[110:111]
	s_waitcnt lgkmcnt(8)
	v_mfma_f32_32x32x16_bf16 v[16:31], v[238:241], v[222:225], v[16:31]
	ds_read_b64_tr_b16 v[222:223], v3 offset:15360
	ds_read_b64_tr_b16 v[224:225], v3 offset:17920
	v_cvt_pk_bf16_f32 v246, v116, v117
	v_cvt_pk_bf16_f32 v247, v118, v119
	s_waitcnt lgkmcnt(8)
	v_mfma_f32_32x32x16_bf16 v[64:79], v[244:247], v[226:229], v[64:79]
	ds_read_b64_tr_b16 v[226:227], v3 offset:15424
	ds_read_b64_tr_b16 v[228:229], v3 offset:17984
	v_exp_f32_e32 v120, v120
	v_exp_f32_e32 v121, v121
	v_exp_f32_e32 v122, v122
	v_pk_add_f32 v[252:253], v[252:253], v[112:113]
	s_waitcnt lgkmcnt(8)
	v_mfma_f32_32x32x16_bf16 v[48:63], v[244:247], v[230:233], v[48:63]
	ds_read_b64_tr_b16 v[230:231], v3 offset:15488
	ds_read_b64_tr_b16 v[232:233], v3 offset:18048
	v_exp_f32_e32 v123, v123
	v_exp_f32_e32 v124, v124
	v_exp_f32_e32 v125, v125
	v_cvt_pk_bf16_f32 v248, v120, v121
	v_pk_add_f32 v[252:253], v[252:253], v[114:115]
	s_waitcnt lgkmcnt(8)
	v_mfma_f32_32x32x16_bf16 v[32:47], v[244:247], v[214:217], v[32:47]
	ds_read_b64_tr_b16 v[214:215], v3 offset:15552
	ds_read_b64_tr_b16 v[216:217], v3 offset:18112
	v_exp_f32_e32 v126, v126
	v_exp_f32_e32 v127, v127
	v_cvt_pk_bf16_f32 v249, v122, v123
	v_pk_add_f32 v[252:253], v[252:253], v[116:117]
	v_pk_add_f32 v[252:253], v[252:253], v[118:119]
	s_waitcnt lgkmcnt(8)
	v_mfma_f32_32x32x16_bf16 v[16:31], v[244:247], v[218:221], v[16:31]
	v_cvt_pk_bf16_f32 v250, v124, v125
	v_cvt_pk_bf16_f32 v251, v126, v127
	s_waitcnt lgkmcnt(6)
	v_mfma_f32_32x32x16_bf16 v[64:79], v[248:251], v[222:225], v[64:79]
	v_pk_add_f32 v[252:253], v[252:253], v[120:121]
	v_pk_add_f32 v[252:253], v[252:253], v[122:123]
	v_pk_add_f32 v[252:253], v[252:253], v[124:125]
	s_waitcnt lgkmcnt(4)
	v_mfma_f32_32x32x16_bf16 v[48:63], v[248:251], v[226:229], v[48:63]
	v_pk_add_f32 v[252:253], v[252:253], v[126:127]
	s_waitcnt lgkmcnt(2)
	v_mfma_f32_32x32x16_bf16 v[32:47], v[248:251], v[230:233], v[32:47]
	v_add_f32_e32 v252, v252, v253
	s_waitcnt lgkmcnt(0)
	v_mfma_f32_32x32x16_bf16 v[16:31], v[248:251], v[214:217], v[16:31]
	v_add_f32_e32 v2, v2, v252
	s_setprio 0
